# V address calc, first V reads and first-half max tree moved into the QK k2=1 MFMA gaps
# speedup vs baseline: 1.0584x; 1.0017x over previous
; #define MFMA(a, b, c) __builtin_amdgcn_mfma_f32_32x32x16_bf16((a), (b), (c), 0, 0, 0)
; DEV int crow_of(int reg, int h) { return (reg & 3) + 8 * (reg >> 2) + 4 * h; }
; template <int DQK, int DV, int NKH, int MODE>
; DEV void flash_unit(const FlashArgs& fa, char* smem, f32x16 (&oacc)[DV / 32], float& linv_out) {
;     ...
;       for (int k2 = 0; k2 < 2; ++k2) {
; #pragma unroll
;         for (int s = 0; s < NS; ++s) {
;           const bf16x8 kf = kfr[k2][s];
;           if (s == 0) st[k2] = MFMA(kf, qf[s], negm);
;           else st[k2] = MFMA(kf, qf[s], st[k2]);
;           constexpr int NQK = 2 * NS, EVERY = NQK / LPT;
;           const int m = k2 * NS + s;
;           if ((m + 1) % EVERY == 0 && (m + 1) / EVERY <= LPT) {
;             __builtin_amdgcn_sched_barrier(0);
;             if (pre) issue_piece(it + 3, (m + 1) / EVERY - 1);
;             __builtin_amdgcn_sched_barrier(0);
;           }
;         }
;       }
;       if (MODE == 1 && it >= 4) {
;         const int dr = krow - na_row + 7;
;         const float* bp = rpbs + dr * 31;
; #pragma unroll
;         for (int k2 = 0; k2 < 2; ++k2)
; #pragma unroll
;           for (int e = 0; e < 16; ++e) {
;             const int kc = k2 * 32 + crow_of(e, h);
;             const bool valid = (kc >= na_cstart) && (kc < na_cstart + 16);
;             const int idx = min(max(kc - na_qc + 15, 0), 30);
;             const float bv = bp[idx];
;             st[k2][e] = valid ? st[k2][e] + bv : -1e30f;
;           }
;       }
;       float rel = st[0][0];
; #pragma unroll
;       for (int e = 1; e < 16; ++e) rel = fmaxf(rel, st[0][e]);
; #pragma unroll
;       for (int e = 0; e < 16; ++e) rel = fmaxf(rel, st[1][e]);
;       rel = half_max(rel);
.Ldf_d2:
	v_mfma_f32_32x32x16_bf16 v[80:95], v[136:139], v[120:123], v[64:79]
	v_add3_u32 v251, v194, v195, v196
	v_add3_u32 v252, v194, v197, v196
	v_add3_u32 v247, s16, v190, v251
	v_add3_u32 v248, s16, v190, v252
	v_add3_u32 v249, s16, v191, v251
	v_add3_u32 v250, s16, v191, v252
	ds_read_b64_tr_b16 v[136:137], v247 offset:16384
	ds_read_b64_tr_b16 v[138:139], v248 offset:18432
	v_mfma_f32_32x32x16_bf16 v[80:95], v[140:143], v[112:115], v[80:95]
	v_add3_u32 v243, s16, v188, v251
	v_add3_u32 v244, s16, v188, v252
	v_add3_u32 v245, s16, v189, v251
	v_add3_u32 v246, s16, v189, v252
	ds_read_b64_tr_b16 v[140:141], v249 offset:16384
	ds_read_b64_tr_b16 v[142:143], v250 offset:18432
	s_cmp_ge_u32 s4, s11
	s_cbranch_scc1 .Ldf_d3
	s_add_i32 m0, s1, 0x4000
	s_nop 0
	global_load_lds_dwordx4 v[160:161], off
.Ldf_d3:
	v_mfma_f32_32x32x16_bf16 v[80:95], v[128:131], v[116:119], v[80:95]
	ds_read_b64_tr_b16 v[128:129], v243 offset:16384
	ds_read_b64_tr_b16 v[130:131], v244 offset:18432
	v_max3_f32 v252, v96, v97, v98
	v_max3_f32 v251, v99, v100, v101
	v_max3_f32 v254, v102, v103, v104
	v_max3_f32 v144, v105, v106, v107
	s_waitcnt lgkmcnt(6)
	v_mfma_f32_32x32x16_bf16 v[80:95], v[132:135], v[124:127], v[80:95]
	ds_read_b64_tr_b16 v[132:133], v245 offset:16384
	ds_read_b64_tr_b16 v[134:135], v246 offset:18432
	v_max3_f32 v252, v252, v108, v109
	v_max3_f32 v251, v251, v110, v111
	s_cmp_ge_u32 s4, s11
	s_cbranch_scc1 .LBB0_88
	s_add_i32 m0, s1, 0x6000
	s_nop 0
	global_load_lds_dwordx4 v[158:159], off
.LBB0_88:
	s_nop 5
	v_max3_f32 v254, v254, v80, v81
	v_max3_f32 v144, v144, v82, v83
	v_max3_f32 v252, v252, v84, v85
	v_max3_f32 v251, v251, v86, v87
	v_max3_f32 v254, v254, v88, v89
	v_max3_f32 v144, v144, v90, v91
	v_max3_f32 v252, v252, v92, v93
	v_max3_f32 v251, v251, v94, v95
	v_max3_f32 v252, v252, v251, v254
	v_max_f32_e32 v252, v252, v144
	v_cmp_lt_f32_e32 vcc, s33, v252
	s_cbranch_vccz .LBB0_90
	v_mov_b32_e32 v251, v252
	s_nop 1
	v_permlane32_swap_b32_e32 v252, v251
	v_max_f32_e32 v252, v252, v251
	v_max_f32_e32 v64, 0, v252
	v_exp_f32_e64 v66, -v64
	v_add_f32_e32 v157, v157, v64
	v_pk_add_f32 v[96:97], v[96:97], v[64:65] op_sel_hi:[1,0] neg_lo:[0,1] neg_hi:[0,1]
	v_pk_add_f32 v[98:99], v[98:99], v[64:65] op_sel_hi:[1,0] neg_lo:[0,1] neg_hi:[0,1]
	v_pk_add_f32 v[100:101], v[100:101], v[64:65] op_sel_hi:[1,0] neg_lo:[0,1] neg_hi:[0,1]
	v_pk_add_f32 v[102:103], v[102:103], v[64:65] op_sel_hi:[1,0] neg_lo:[0,1] neg_hi:[0,1]
	v_pk_add_f32 v[104:105], v[104:105], v[64:65] op_sel_hi:[1,0] neg_lo:[0,1] neg_hi:[0,1]
	v_pk_add_f32 v[106:107], v[106:107], v[64:65] op_sel_hi:[1,0] neg_lo:[0,1] neg_hi:[0,1]
	v_pk_add_f32 v[108:109], v[108:109], v[64:65] op_sel_hi:[1,0] neg_lo:[0,1] neg_hi:[0,1]
	v_pk_add_f32 v[110:111], v[110:111], v[64:65] op_sel_hi:[1,0] neg_lo:[0,1] neg_hi:[0,1]
	v_pk_add_f32 v[80:81], v[80:81], v[64:65] op_sel_hi:[1,0] neg_lo:[0,1] neg_hi:[0,1]
	v_pk_add_f32 v[82:83], v[82:83], v[64:65] op_sel_hi:[1,0] neg_lo:[0,1] neg_hi:[0,1]
	v_pk_add_f32 v[84:85], v[84:85], v[64:65] op_sel_hi:[1,0] neg_lo:[0,1] neg_hi:[0,1]
	v_pk_add_f32 v[86:87], v[86:87], v[64:65] op_sel_hi:[1,0] neg_lo:[0,1] neg_hi:[0,1]
	v_pk_add_f32 v[88:89], v[88:89], v[64:65] op_sel_hi:[1,0] neg_lo:[0,1] neg_hi:[0,1]
	v_pk_add_f32 v[90:91], v[90:91], v[64:65] op_sel_hi:[1,0] neg_lo:[0,1] neg_hi:[0,1]
	v_pk_add_f32 v[92:93], v[92:93], v[64:65] op_sel_hi:[1,0] neg_lo:[0,1] neg_hi:[0,1]
	v_pk_add_f32 v[94:95], v[94:95], v[64:65] op_sel_hi:[1,0] neg_lo:[0,1] neg_hi:[0,1]
	v_xor_b32_e32 v64, 0x80000000, v157
	v_pk_mul_f32 v[46:47], v[46:47], v[66:67] op_sel_hi:[1,0]
	v_pk_mul_f32 v[44:45], v[44:45], v[66:67] op_sel_hi:[1,0]
	v_pk_mul_f32 v[42:43], v[42:43], v[66:67] op_sel_hi:[1,0]
	v_pk_mul_f32 v[40:41], v[40:41], v[66:67] op_sel_hi:[1,0]
	v_pk_mul_f32 v[38:39], v[38:39], v[66:67] op_sel_hi:[1,0]
	v_pk_mul_f32 v[36:37], v[36:37], v[66:67] op_sel_hi:[1,0]
	v_pk_mul_f32 v[34:35], v[34:35], v[66:67] op_sel_hi:[1,0]
	v_pk_mul_f32 v[32:33], v[32:33], v[66:67] op_sel_hi:[1,0]
	v_pk_mul_f32 v[62:63], v[62:63], v[66:67] op_sel_hi:[1,0]
	v_pk_mul_f32 v[60:61], v[60:61], v[66:67] op_sel_hi:[1,0]
	v_pk_mul_f32 v[58:59], v[58:59], v[66:67] op_sel_hi:[1,0]
	v_pk_mul_f32 v[56:57], v[56:57], v[66:67] op_sel_hi:[1,0]
	v_pk_mul_f32 v[54:55], v[54:55], v[66:67] op_sel_hi:[1,0]
	v_pk_mul_f32 v[52:53], v[52:53], v[66:67] op_sel_hi:[1,0]
	v_pk_mul_f32 v[50:51], v[50:51], v[66:67] op_sel_hi:[1,0]
	v_pk_mul_f32 v[48:49], v[48:49], v[66:67] op_sel_hi:[1,0]
	v_pk_mul_f32 v[30:31], v[30:31], v[66:67] op_sel_hi:[1,0]
	v_pk_mul_f32 v[28:29], v[28:29], v[66:67] op_sel_hi:[1,0]
	v_pk_mul_f32 v[26:27], v[26:27], v[66:67] op_sel_hi:[1,0]
	v_pk_mul_f32 v[24:25], v[24:25], v[66:67] op_sel_hi:[1,0]
	v_pk_mul_f32 v[22:23], v[22:23], v[66:67] op_sel_hi:[1,0]
	v_pk_mul_f32 v[20:21], v[20:21], v[66:67] op_sel_hi:[1,0]
	v_pk_mul_f32 v[18:19], v[18:19], v[66:67] op_sel_hi:[1,0]
	v_pk_mul_f32 v[16:17], v[16:17], v[66:67] op_sel_hi:[1,0]
	v_pk_mul_f32 v[14:15], v[14:15], v[66:67] op_sel_hi:[1,0]
	v_pk_mul_f32 v[12:13], v[12:13], v[66:67] op_sel_hi:[1,0]
	v_pk_mul_f32 v[10:11], v[10:11], v[66:67] op_sel_hi:[1,0]
	v_pk_mul_f32 v[8:9], v[8:9], v[66:67] op_sel_hi:[1,0]
	v_pk_mul_f32 v[6:7], v[6:7], v[66:67] op_sel_hi:[1,0]
	v_pk_mul_f32 v[4:5], v[4:5], v[66:67] op_sel_hi:[1,0]
	v_pk_mul_f32 v[2:3], v[2:3], v[66:67] op_sel_hi:[1,0]
	v_pk_mul_f32 v[0:1], v[0:1], v[66:67] op_sel_hi:[1,0]
	v_mul_f32_e32 v156, v156, v66
	v_mov_b32_e32 v65, v64
	v_mov_b32_e32 v66, v64
	v_mov_b32_e32 v67, v64
	v_mov_b32_e32 v68, v64
	v_mov_b32_e32 v69, v64
	v_mov_b32_e32 v70, v64
	v_mov_b32_e32 v71, v64
	v_mov_b32_e32 v72, v64
	v_mov_b32_e32 v73, v64
	v_mov_b32_e32 v74, v64
	v_mov_b32_e32 v75, v64
	v_mov_b32_e32 v76, v64
	v_mov_b32_e32 v77, v64
	v_mov_b32_e32 v78, v64
	v_mov_b32_e32 v79, v64
; #define MFMA(a, b, c) __builtin_amdgcn_mfma_f32_32x32x16_bf16((a), (b), (c), 0, 0, 0)
; DEV float fast_exp2(float x) { return __builtin_amdgcn_exp2f(x); }
; template <int DQK, int DV, int NKH, int MODE>
; DEV void flash_unit(const FlashArgs& fa, char* smem, f32x16 (&oacc)[DV / 32], float& linv_out) {
;     ...
;       float psum = 0.f;
; #pragma unroll
;       for (int k2 = 0; k2 < 2; ++k2)
; #pragma unroll
;         for (int e = 0; e < 16; ++e) { st[k2][e] = fast_exp2(st[k2][e]); psum += st[k2][e]; }
;       lrun += psum;
;       bf16x8 pf[2][2];
; #pragma unroll
;       for (int k2 = 0; k2 < 2; ++k2)
; #pragma unroll
;         for (int s2 = 0; s2 < 2; ++s2) {
;           uint4 u = make_uint4(pk2(st[k2][8 * s2], st[k2][8 * s2 + 1]), pk2(st[k2][8 * s2 + 2], st[k2][8 * s2 + 3]),
;                                pk2(st[k2][8 * s2 + 4], st[k2][8 * s2 + 5]), pk2(st[k2][8 * s2 + 6], st[k2][8 * s2 + 7]));
;           pf[k2][s2] = __builtin_bit_cast(bf16x8, u);
;         }
; #pragma unroll
;       for (int v = 0; v < NV; ++v)
; #pragma unroll
;         for (int k2 = 0; k2 < 2; ++k2)
; #pragma unroll
;           for (int s2 = 0; s2 < 2; ++s2) {
;             const char* a1 = vb + (k2 * 32 + s2 * 16) * VROW + vhi[v] + vlow0;
;             const char* a2 = vb + (k2 * 32 + s2 * 16 + 8) * VROW + vhi[v] + vlow1;
;             s16x4 lo = __builtin_amdgcn_ds_read_tr16_b64_v4i16((__attribute__((address_space(3))) s16x4*)(a1));
;             s16x4 hi = __builtin_amdgcn_ds_read_tr16_b64_v4i16((__attribute__((address_space(3))) s16x4*)(a2));
;             const bf16x8 vf = __builtin_shufflevector(lo, hi, 0, 1, 2, 3, 4, 5, 6, 7);
;             oacc[v] = MFMA(vf, pf[k2][s2], oacc[v]);
;           }
.LBB0_90:
	v_exp_f32_e32 v96, v96
	v_exp_f32_e32 v97, v97
	v_exp_f32_e32 v98, v98
	v_exp_f32_e32 v99, v99
	v_add_f32_e32 v253, v96, v97
	v_exp_f32_e32 v100, v100
	v_cvt_pk_bf16_f32 v96, v96, v97
	v_exp_f32_e32 v101, v101
	v_add_f32_e32 v253, v253, v98
	v_exp_f32_e32 v102, v102
	v_add_f32_e32 v253, v253, v99
	v_exp_f32_e32 v103, v103
	v_cvt_pk_bf16_f32 v97, v98, v99
	v_add_f32_e32 v253, v253, v100
	v_cvt_pk_bf16_f32 v98, v100, v101
	v_add_f32_e32 v253, v253, v101
	v_cvt_pk_bf16_f32 v99, v102, v103
	v_add_f32_e32 v253, v253, v102
	v_add_f32_e32 v253, v253, v103
	s_waitcnt lgkmcnt(2)
	v_mfma_f32_32x32x16_bf16 v[32:47], v[128:131], v[96:99], v[32:47]
	v_exp_f32_e32 v104, v104
	v_exp_f32_e32 v105, v105
	ds_read_b64_tr_b16 v[128:129], v243 offset:20480
	v_add_f32_e32 v253, v253, v104
	v_cvt_pk_bf16_f32 v104, v104, v105
	ds_read_b64_tr_b16 v[130:131], v244 offset:22528
	v_add_f32_e32 v253, v253, v105
	s_waitcnt lgkmcnt(2)
	v_mfma_f32_32x32x16_bf16 v[48:63], v[132:135], v[96:99], v[48:63]
	v_exp_f32_e32 v106, v106
	v_exp_f32_e32 v107, v107
	ds_read_b64_tr_b16 v[132:133], v245 offset:20480
	v_add_f32_e32 v253, v253, v106
	v_cvt_pk_bf16_f32 v105, v106, v107
	ds_read_b64_tr_b16 v[134:135], v246 offset:22528
	v_add_f32_e32 v253, v253, v107
	s_waitcnt lgkmcnt(6)
	v_mfma_f32_32x32x16_bf16 v[16:31], v[136:139], v[96:99], v[16:31]
	v_exp_f32_e32 v108, v108
	v_exp_f32_e32 v109, v109
	ds_read_b64_tr_b16 v[136:137], v247 offset:20480
	v_add_f32_e32 v253, v253, v108
	v_cvt_pk_bf16_f32 v106, v108, v109
	ds_read_b64_tr_b16 v[138:139], v248 offset:22528
	v_add_f32_e32 v253, v253, v109
	s_waitcnt lgkmcnt(6)
	v_mfma_f32_32x32x16_bf16 v[0:15], v[140:143], v[96:99], v[0:15]
	v_exp_f32_e32 v110, v110
	v_exp_f32_e32 v111, v111
	ds_read_b64_tr_b16 v[140:141], v249 offset:20480
	v_add_f32_e32 v253, v253, v110
	v_cvt_pk_bf16_f32 v107, v110, v111
	ds_read_b64_tr_b16 v[142:143], v250 offset:22528
	v_add_f32_e32 v253, v253, v111
	s_waitcnt lgkmcnt(6)
	v_mfma_f32_32x32x16_bf16 v[32:47], v[128:131], v[104:107], v[32:47]
	v_exp_f32_e32 v80, v80
	v_exp_f32_e32 v81, v81
	ds_read_b64_tr_b16 v[128:129], v243 offset:24576
	v_add_f32_e32 v253, v253, v80
	v_cvt_pk_bf16_f32 v80, v80, v81
	ds_read_b64_tr_b16 v[130:131], v244 offset:26624
	v_add_f32_e32 v253, v253, v81
	s_waitcnt lgkmcnt(6)
	v_mfma_f32_32x32x16_bf16 v[48:63], v[132:135], v[104:107], v[48:63]
	v_exp_f32_e32 v82, v82
	v_exp_f32_e32 v83, v83
	ds_read_b64_tr_b16 v[132:133], v245 offset:24576
	v_add_f32_e32 v253, v253, v82
	v_cvt_pk_bf16_f32 v81, v82, v83
	ds_read_b64_tr_b16 v[134:135], v246 offset:26624
	v_add_f32_e32 v253, v253, v83
	s_waitcnt lgkmcnt(6)
	v_mfma_f32_32x32x16_bf16 v[16:31], v[136:139], v[104:107], v[16:31]
	v_exp_f32_e32 v84, v84
	v_exp_f32_e32 v85, v85
	ds_read_b64_tr_b16 v[136:137], v247 offset:24576
	v_add_f32_e32 v253, v253, v84
	v_cvt_pk_bf16_f32 v82, v84, v85
	ds_read_b64_tr_b16 v[138:139], v248 offset:26624
	v_add_f32_e32 v253, v253, v85
	s_waitcnt lgkmcnt(6)
	v_mfma_f32_32x32x16_bf16 v[0:15], v[140:143], v[104:107], v[0:15]
	v_exp_f32_e32 v86, v86
	v_exp_f32_e32 v87, v87
	ds_read_b64_tr_b16 v[140:141], v249 offset:24576
	v_add_f32_e32 v253, v253, v86
	v_cvt_pk_bf16_f32 v83, v86, v87
	ds_read_b64_tr_b16 v[142:143], v250 offset:26624
	v_add_f32_e32 v253, v253, v87
	s_waitcnt lgkmcnt(6)
	v_mfma_f32_32x32x16_bf16 v[32:47], v[128:131], v[80:83], v[32:47]
	v_exp_f32_e32 v88, v88
	v_exp_f32_e32 v89, v89
	ds_read_b64_tr_b16 v[128:129], v243 offset:28672
	v_add_f32_e32 v253, v253, v88
	v_cvt_pk_bf16_f32 v88, v88, v89
	ds_read_b64_tr_b16 v[130:131], v244 offset:30720
	v_add_f32_e32 v253, v253, v89
	s_waitcnt lgkmcnt(6)
	v_mfma_f32_32x32x16_bf16 v[48:63], v[132:135], v[80:83], v[48:63]
	v_exp_f32_e32 v90, v90
	v_exp_f32_e32 v91, v91
	ds_read_b64_tr_b16 v[132:133], v245 offset:28672
	v_add_f32_e32 v253, v253, v90
	v_cvt_pk_bf16_f32 v89, v90, v91
	ds_read_b64_tr_b16 v[134:135], v246 offset:30720
	v_add_f32_e32 v253, v253, v91
	s_waitcnt lgkmcnt(6)
	v_mfma_f32_32x32x16_bf16 v[16:31], v[136:139], v[80:83], v[16:31]
	v_exp_f32_e32 v92, v92
	v_exp_f32_e32 v93, v93
	ds_read_b64_tr_b16 v[136:137], v247 offset:28672
	v_add_f32_e32 v253, v253, v92
	v_cvt_pk_bf16_f32 v90, v92, v93
	ds_read_b64_tr_b16 v[138:139], v248 offset:30720
	v_add_f32_e32 v253, v253, v93
	s_waitcnt lgkmcnt(6)
	v_mfma_f32_32x32x16_bf16 v[0:15], v[140:143], v[80:83], v[0:15]
	v_exp_f32_e32 v94, v94
	v_exp_f32_e32 v95, v95
	ds_read_b64_tr_b16 v[140:141], v249 offset:28672
	v_add_f32_e32 v253, v253, v94
	v_cvt_pk_bf16_f32 v91, v94, v95
	ds_read_b64_tr_b16 v[142:143], v250 offset:30720
	v_add_f32_e32 v253, v253, v95
	s_waitcnt lgkmcnt(6)
	v_mfma_f32_32x32x16_bf16 v[32:47], v[128:131], v[88:91], v[32:47]
	v_add_f32_e32 v156, v156, v253
	v_lshl_add_u64 v[158:159], v[158:159], 0, v[154:155]
	s_waitcnt lgkmcnt(4)
	v_mfma_f32_32x32x16_bf16 v[48:63], v[132:135], v[88:91], v[48:63]
	v_lshl_add_u64 v[160:161], v[160:161], 0, v[152:153]
	v_lshl_add_u64 v[162:163], v[162:163], 0, v[150:151]
	s_waitcnt lgkmcnt(2)
	v_mfma_f32_32x32x16_bf16 v[16:31], v[136:139], v[88:91], v[16:31]
	v_lshl_add_u64 v[164:165], v[164:165], 0, v[148:149]
	s_add_i32 s4, s4, 1
	s_add_i32 s14, s14, -1
	s_waitcnt lgkmcnt(0)
	v_mfma_f32_32x32x16_bf16 v[0:15], v[140:143], v[88:91], v[0:15]
	s_cmp_lg_u32 s5, s15
	s_cbranch_scc1 .LBB0_72
	v_and_b32_e32 v65, 64, v175
	v_xor_b32_e32 v64, 32, v175
	v_add_u32_e32 v65, 64, v65
	v_cmp_lt_i32_e32 vcc, v64, v65
	v_and_b32_e32 v65, 63, v182
	v_ashrrev_i32_e32 v120, 6, v182
	v_cndmask_b32_e32 v64, v175, v64, vcc
	v_lshlrev_b32_e32 v69, 2, v64
	ds_bpermute_b32 v64, v69, v156
	v_cmp_lt_i32_e32 vcc, 3, v120
	s_barrier
; DEV void attn_diff_unit(const Params& p, int l, int bl, int hd, int q_t0, int n_tiles, char* smem) {
;     ...
;   float* xb = (float*)smem;
;   if (w >= 4) {
; #pragma unroll
;     for (int v = 0; v < 4; ++v)
; #pragma unroll
;       for (int e = 0; e < 16; ++e) xb[((w - 4) * 64 + v * 16 + e) * 64 + lane] = o[v][e] * linv;
;   }
	s_waitcnt lgkmcnt(0)
	v_add_f32_e32 v64, v156, v64
	v_rcp_f32_e32 v68, v64
	v_lshlrev_b32_e32 v64, 2, v65
	v_lshlrev_b32_e32 v65, 8, v182
	v_and_b32_e32 v65, 0xffffc000, v65
	s_and_saveexec_b64 s[0:1], vcc
	s_cbranch_execz .LBB0_93
	v_add3_u32 v67, 0, v64, v65
	v_mul_f32_e32 v66, v32, v68
	v_add_u32_e32 v70, 0xffff0000, v67
	ds_write_b32 v70, v66
	v_mul_f32_e32 v66, v33, v68
	v_add_u32_e32 v70, 0xffff0100, v67
	ds_write_b32 v70, v66
	v_mul_f32_e32 v66, v34, v68
	v_add_u32_e32 v70, 0xffff0200, v67
	ds_write_b32 v70, v66
	v_mul_f32_e32 v66, v35, v68
	v_add_u32_e32 v70, 0xffff0300, v67
	ds_write_b32 v70, v66
	v_mul_f32_e32 v66, v36, v68
	v_add_u32_e32 v70, 0xffff0400, v67
	ds_write_b32 v70, v66
	v_mul_f32_e32 v66, v37, v68
	v_add_u32_e32 v70, 0xffff0500, v67
	ds_write_b32 v70, v66
	v_mul_f32_e32 v66, v38, v68
	v_add_u32_e32 v70, 0xffff0600, v67
	ds_write_b32 v70, v66
	v_mul_f32_e32 v66, v39, v68
	v_add_u32_e32 v70, 0xffff0700, v67
	ds_write_b32 v70, v66
	v_mul_f32_e32 v66, v40, v68
	v_add_u32_e32 v70, 0xffff0800, v67
	ds_write_b32 v70, v66
	v_mul_f32_e32 v66, v41, v68
	v_add_u32_e32 v70, 0xffff0900, v67
	ds_write_b32 v70, v66
	v_mul_f32_e32 v66, v42, v68
	v_add_u32_e32 v70, 0xffff0a00, v67
	ds_write_b32 v70, v66
	v_mul_f32_e32 v66, v43, v68
	v_add_u32_e32 v70, 0xffff0b00, v67
	ds_write_b32 v70, v66
	v_mul_f32_e32 v66, v44, v68
	v_add_u32_e32 v70, 0xffff0c00, v67
	ds_write_b32 v70, v66
	v_mul_f32_e32 v66, v45, v68
	v_add_u32_e32 v70, 0xffff0d00, v67
	ds_write_b32 v70, v66
	v_mul_f32_e32 v66, v46, v68
	v_add_u32_e32 v70, 0xffff0e00, v67
	ds_write_b32 v70, v66
	v_mul_f32_e32 v66, v47, v68
	v_add_u32_e32 v70, 0xffff0f00, v67
	ds_write_b32 v70, v66
	v_mul_f32_e32 v66, v48, v68
	v_add_u32_e32 v70, 0xffff1000, v67
	ds_write_b32 v70, v66
	v_mul_f32_e32 v66, v49, v68
	v_add_u32_e32 v70, 0xffff1100, v67
	ds_write_b32 v70, v66
	v_mul_f32_e32 v66, v50, v68
	v_add_u32_e32 v70, 0xffff1200, v67
	ds_write_b32 v70, v66
	v_mul_f32_e32 v66, v51, v68
	v_add_u32_e32 v70, 0xffff1300, v67
	ds_write_b32 v70, v66
	v_mul_f32_e32 v66, v52, v68
	v_add_u32_e32 v70, 0xffff1400, v67
	ds_write_b32 v70, v66
	v_mul_f32_e32 v66, v53, v68
	v_add_u32_e32 v70, 0xffff1500, v67
	ds_write_b32 v70, v66
	v_mul_f32_e32 v66, v54, v68
	v_add_u32_e32 v70, 0xffff1600, v67
	ds_write_b32 v70, v66
	v_mul_f32_e32 v66, v55, v68
	v_add_u32_e32 v70, 0xffff1700, v67
	ds_write_b32 v70, v66
	v_mul_f32_e32 v66, v56, v68
	v_add_u32_e32 v70, 0xffff1800, v67
	ds_write_b32 v70, v66
	v_mul_f32_e32 v66, v57, v68
	v_add_u32_e32 v70, 0xffff1900, v67
	ds_write_b32 v70, v66
	v_mul_f32_e32 v66, v58, v68
	v_add_u32_e32 v70, 0xffff1a00, v67
	ds_write_b32 v70, v66
	v_mul_f32_e32 v66, v59, v68
	v_add_u32_e32 v70, 0xffff1b00, v67
	ds_write_b32 v70, v66
	v_mul_f32_e32 v66, v60, v68
	v_add_u32_e32 v70, 0xffff1c00, v67
	ds_write_b32 v70, v66
	v_mul_f32_e32 v66, v61, v68
	v_add_u32_e32 v70, 0xffff1d00, v67
	ds_write_b32 v70, v66
	v_mul_f32_e32 v66, v62, v68
	v_add_u32_e32 v70, 0xffff1e00, v67
	ds_write_b32 v70, v66
	v_mul_f32_e32 v66, v63, v68
	v_add_u32_e32 v70, 0xffff1f00, v67
	ds_write_b32 v70, v66
	v_mul_f32_e32 v66, v16, v68
	v_add_u32_e32 v70, 0xffff2000, v67
	ds_write_b32 v70, v66
	v_mul_f32_e32 v66, v17, v68
	v_add_u32_e32 v70, 0xffff2100, v67
	ds_write_b32 v70, v66
	v_mul_f32_e32 v66, v18, v68
	v_add_u32_e32 v70, 0xffff2200, v67
	ds_write_b32 v70, v66
	v_mul_f32_e32 v66, v19, v68
	v_add_u32_e32 v70, 0xffff2300, v67
	ds_write_b32 v70, v66
	v_mul_f32_e32 v66, v20, v68
	v_add_u32_e32 v70, 0xffff2400, v67
	ds_write_b32 v70, v66
	v_mul_f32_e32 v66, v21, v68
	v_add_u32_e32 v70, 0xffff2500, v67
	ds_write_b32 v70, v66
	v_mul_f32_e32 v66, v22, v68
	v_add_u32_e32 v70, 0xffff2600, v67
	ds_write_b32 v70, v66
	v_mul_f32_e32 v66, v23, v68
	v_add_u32_e32 v70, 0xffff2700, v67
	ds_write_b32 v70, v66
	v_mul_f32_e32 v66, v24, v68
	v_add_u32_e32 v70, 0xffff2800, v67
	ds_write_b32 v70, v66
	v_mul_f32_e32 v66, v25, v68
	v_add_u32_e32 v70, 0xffff2900, v67
	ds_write_b32 v70, v66
	v_mul_f32_e32 v66, v26, v68
	v_add_u32_e32 v70, 0xffff2a00, v67
	ds_write_b32 v70, v66
	v_mul_f32_e32 v66, v27, v68
	v_add_u32_e32 v70, 0xffff2b00, v67
	ds_write_b32 v70, v66
	v_mul_f32_e32 v66, v28, v68
	v_add_u32_e32 v70, 0xffff2c00, v67
	ds_write_b32 v70, v66
	v_mul_f32_e32 v66, v29, v68
	v_add_u32_e32 v70, 0xffff2d00, v67
	ds_write_b32 v70, v66
	v_mul_f32_e32 v66, v30, v68
	v_add_u32_e32 v70, 0xffff2e00, v67
	ds_write_b32 v70, v66
	v_mul_f32_e32 v66, v31, v68
	v_add_u32_e32 v70, 0xffff2f00, v67
	ds_write_b32 v70, v66
	v_mul_f32_e32 v66, v0, v68
	v_add_u32_e32 v70, 0xffff3000, v67
	ds_write_b32 v70, v66
	v_mul_f32_e32 v66, v1, v68
	v_add_u32_e32 v70, 0xffff3100, v67
	ds_write_b32 v70, v66
	v_mul_f32_e32 v66, v2, v68
	v_add_u32_e32 v70, 0xffff3200, v67
	ds_write_b32 v70, v66
	v_mul_f32_e32 v66, v3, v68
	v_add_u32_e32 v70, 0xffff3300, v67
	ds_write_b32 v70, v66
	v_mul_f32_e32 v66, v4, v68
	v_add_u32_e32 v70, 0xffff3400, v67
	ds_write_b32 v70, v66
	v_mul_f32_e32 v66, v5, v68
	v_add_u32_e32 v70, 0xffff3500, v67
	ds_write_b32 v70, v66
	v_mul_f32_e32 v66, v6, v68
	v_add_u32_e32 v70, 0xffff3600, v67
	ds_write_b32 v70, v66
	v_mul_f32_e32 v66, v7, v68
	v_add_u32_e32 v70, 0xffff3700, v67
	ds_write_b32 v70, v66
	v_mul_f32_e32 v66, v8, v68
	v_add_u32_e32 v70, 0xffff3800, v67
	ds_write_b32 v70, v66
	v_mul_f32_e32 v66, v9, v68
	v_add_u32_e32 v70, 0xffff3900, v67
	ds_write_b32 v70, v66
	v_mul_f32_e32 v66, v10, v68
	v_add_u32_e32 v70, 0xffff3a00, v67
	ds_write_b32 v70, v66
	v_mul_f32_e32 v66, v11, v68
	v_add_u32_e32 v70, 0xffff3b00, v67
	ds_write_b32 v70, v66
	v_mul_f32_e32 v66, v12, v68
	v_add_u32_e32 v70, 0xffff3c00, v67
	ds_write_b32 v70, v66
	v_mul_f32_e32 v66, v13, v68
	v_add_u32_e32 v70, 0xffff3d00, v67
	ds_write_b32 v70, v66
	v_mul_f32_e32 v66, v14, v68
	v_add_u32_e32 v70, 0xffff3e00, v67
	ds_write_b32 v70, v66
	v_mul_f32_e32 v66, v15, v68
	v_add_u32_e32 v67, 0xffff3f00, v67
	ds_write_b32 v67, v66

; #define MFMA(a, b, c) __builtin_amdgcn_mfma_f32_32x32x16_bf16((a), (b), (c), 0, 0, 0)
; DEV int crow_of(int reg, int h) { return (reg & 3) + 8 * (reg >> 2) + 4 * h; }
; template <int DQK, int DV, int NKH, int MODE>
; DEV void flash_unit(const FlashArgs& fa, char* smem, f32x16 (&oacc)[DV / 32], float& linv_out) {
;     ...
;       for (int k2 = 0; k2 < 2; ++k2) {
; #pragma unroll
;         for (int s = 0; s < NS; ++s) {
;           const bf16x8 kf = kfr[k2][s];
;           if (s == 0) st[k2] = MFMA(kf, qf[s], negm);
;           else st[k2] = MFMA(kf, qf[s], st[k2]);
;           constexpr int NQK = 2 * NS, EVERY = NQK / LPT;
;           const int m = k2 * NS + s;
;           if ((m + 1) % EVERY == 0 && (m + 1) / EVERY <= LPT) {
;             __builtin_amdgcn_sched_barrier(0);
;             if (pre) issue_piece(it + 3, (m + 1) / EVERY - 1);
;             __builtin_amdgcn_sched_barrier(0);
;           }
;         }
;       }
;       if (MODE == 1 && it >= 4) {
;         const int dr = krow - na_row + 7;
;         const float* bp = rpbs + dr * 31;
; #pragma unroll
;         for (int k2 = 0; k2 < 2; ++k2)
; #pragma unroll
;           for (int e = 0; e < 16; ++e) {
;             const int kc = k2 * 32 + crow_of(e, h);
;             const bool valid = (kc >= na_cstart) && (kc < na_cstart + 16);
;             const int idx = min(max(kc - na_qc + 15, 0), 30);
;             const float bv = bp[idx];
;             st[k2][e] = valid ? st[k2][e] + bv : -1e30f;
;           }
;       }
;       float rel = st[0][0];
; #pragma unroll
;       for (int e = 1; e < 16; ++e) rel = fmaxf(rel, st[0][e]);
; #pragma unroll
;       for (int e = 0; e < 16; ++e) rel = fmaxf(rel, st[1][e]);
;       rel = half_max(rel);
.Lmla_d2:
	v_add3_u32 v122, s6, v156, v158
	v_add3_u32 v123, s6, v157, v158
	v_mfma_f32_32x32x16_bf16 v[48:63], v[104:107], v[88:91], v[48:63]
	ds_read_b64_tr_b16 v[104:105], v122 offset:12288
	ds_read_b64_tr_b16 v[106:107], v122 offset:13312
	v_mfma_f32_32x32x16_bf16 v[48:63], v[108:111], v[92:95], v[48:63]
	ds_read_b64_tr_b16 v[108:109], v123 offset:12288
	ds_read_b64_tr_b16 v[110:111], v123 offset:13312
	v_max3_f32 v124, v64, v65, v66
	v_max3_f32 v125, v67, v68, v69
	v_max3_f32 v126, v70, v71, v72
	v_max3_f32 v127, v73, v74, v75
	v_mfma_f32_32x32x16_bf16 v[48:63], v[112:115], v[96:99], v[48:63]
	ds_read_b64_tr_b16 v[112:113], v122 offset:14336
	ds_read_b64_tr_b16 v[114:115], v122 offset:15360
	v_max3_f32 v124, v124, v76, v77
	v_max3_f32 v125, v125, v78, v79
	v_mfma_f32_32x32x16_bf16 v[48:63], v[116:119], v[100:103], v[48:63]
	ds_read_b64_tr_b16 v[116:117], v123 offset:14336
	ds_read_b64_tr_b16 v[118:119], v123 offset:15360
	s_cmp_ge_u32 s19, s18
	s_cbranch_scc1 .Lmla_d3
	s_and_b64 vcc, exec, s[38:39]
	s_cbranch_vccnz .Lmla_d3
	s_add_i32 m0, s7, 0x4000
	s_nop 0
	global_load_lds_dwordx4 v[136:137], off
.Lmla_d3:
	s_nop 7
	v_max3_f32 v126, v126, v48, v49
	v_max3_f32 v127, v127, v50, v51
	v_max3_f32 v124, v124, v52, v53
	v_max3_f32 v125, v125, v54, v55
	v_max3_f32 v126, v126, v56, v57
	v_max3_f32 v127, v127, v58, v59
	v_max3_f32 v124, v124, v60, v61
	v_max3_f32 v125, v125, v62, v63
	v_max3_f32 v124, v124, v125, v126
	v_max_f32_e32 v124, v124, v127
	v_cmp_lt_f32_e32 vcc, s33, v124
	s_cbranch_vccz .LBB0_170
	v_mov_b32_e32 v121, v124
	s_nop 1
	v_permlane32_swap_b32_e32 v124, v121
	v_max_f32_e32 v124, v124, v121
	v_max_f32_e32 v32, 0, v124
	v_exp_f32_e64 v34, -v32
	v_add_f32_e32 v135, v135, v32
	v_pk_add_f32 v[64:65], v[64:65], v[32:33] op_sel_hi:[1,0] neg_lo:[0,1] neg_hi:[0,1]
	v_pk_add_f32 v[66:67], v[66:67], v[32:33] op_sel_hi:[1,0] neg_lo:[0,1] neg_hi:[0,1]
	v_pk_add_f32 v[68:69], v[68:69], v[32:33] op_sel_hi:[1,0] neg_lo:[0,1] neg_hi:[0,1]
	v_pk_add_f32 v[70:71], v[70:71], v[32:33] op_sel_hi:[1,0] neg_lo:[0,1] neg_hi:[0,1]
	v_pk_add_f32 v[72:73], v[72:73], v[32:33] op_sel_hi:[1,0] neg_lo:[0,1] neg_hi:[0,1]
	v_pk_add_f32 v[74:75], v[74:75], v[32:33] op_sel_hi:[1,0] neg_lo:[0,1] neg_hi:[0,1]
	v_pk_add_f32 v[76:77], v[76:77], v[32:33] op_sel_hi:[1,0] neg_lo:[0,1] neg_hi:[0,1]
	v_pk_add_f32 v[78:79], v[78:79], v[32:33] op_sel_hi:[1,0] neg_lo:[0,1] neg_hi:[0,1]
	v_pk_add_f32 v[48:49], v[48:49], v[32:33] op_sel_hi:[1,0] neg_lo:[0,1] neg_hi:[0,1]
	v_pk_add_f32 v[50:51], v[50:51], v[32:33] op_sel_hi:[1,0] neg_lo:[0,1] neg_hi:[0,1]
	v_pk_add_f32 v[52:53], v[52:53], v[32:33] op_sel_hi:[1,0] neg_lo:[0,1] neg_hi:[0,1]
	v_pk_add_f32 v[54:55], v[54:55], v[32:33] op_sel_hi:[1,0] neg_lo:[0,1] neg_hi:[0,1]
	v_pk_add_f32 v[56:57], v[56:57], v[32:33] op_sel_hi:[1,0] neg_lo:[0,1] neg_hi:[0,1]
	v_pk_add_f32 v[58:59], v[58:59], v[32:33] op_sel_hi:[1,0] neg_lo:[0,1] neg_hi:[0,1]
	v_pk_add_f32 v[60:61], v[60:61], v[32:33] op_sel_hi:[1,0] neg_lo:[0,1] neg_hi:[0,1]
	v_pk_add_f32 v[62:63], v[62:63], v[32:33] op_sel_hi:[1,0] neg_lo:[0,1] neg_hi:[0,1]
	v_xor_b32_e32 v32, 0x80000000, v135
	v_pk_mul_f32 v[14:15], v[14:15], v[34:35] op_sel_hi:[1,0]
	v_pk_mul_f32 v[12:13], v[12:13], v[34:35] op_sel_hi:[1,0]
	v_pk_mul_f32 v[10:11], v[10:11], v[34:35] op_sel_hi:[1,0]
	v_pk_mul_f32 v[8:9], v[8:9], v[34:35] op_sel_hi:[1,0]
	v_pk_mul_f32 v[6:7], v[6:7], v[34:35] op_sel_hi:[1,0]
	v_pk_mul_f32 v[4:5], v[4:5], v[34:35] op_sel_hi:[1,0]
	v_pk_mul_f32 v[2:3], v[2:3], v[34:35] op_sel_hi:[1,0]
	v_pk_mul_f32 v[0:1], v[0:1], v[34:35] op_sel_hi:[1,0]
	v_pk_mul_f32 v[30:31], v[30:31], v[34:35] op_sel_hi:[1,0]
	v_pk_mul_f32 v[28:29], v[28:29], v[34:35] op_sel_hi:[1,0]
	v_pk_mul_f32 v[26:27], v[26:27], v[34:35] op_sel_hi:[1,0]
	v_pk_mul_f32 v[24:25], v[24:25], v[34:35] op_sel_hi:[1,0]
	v_pk_mul_f32 v[22:23], v[22:23], v[34:35] op_sel_hi:[1,0]
	v_pk_mul_f32 v[20:21], v[20:21], v[34:35] op_sel_hi:[1,0]
	v_pk_mul_f32 v[18:19], v[18:19], v[34:35] op_sel_hi:[1,0]
	v_pk_mul_f32 v[16:17], v[16:17], v[34:35] op_sel_hi:[1,0]
	v_mul_f32_e32 v134, v134, v34
	v_mov_b32_e32 v33, v32
	v_mov_b32_e32 v34, v32
	v_mov_b32_e32 v35, v32
	v_mov_b32_e32 v36, v32
	v_mov_b32_e32 v37, v32
	v_mov_b32_e32 v38, v32
	v_mov_b32_e32 v39, v32
	v_mov_b32_e32 v40, v32
	v_mov_b32_e32 v41, v32
	v_mov_b32_e32 v42, v32
	v_mov_b32_e32 v43, v32
	v_mov_b32_e32 v44, v32
	v_mov_b32_e32 v45, v32
	v_mov_b32_e32 v46, v32
	v_mov_b32_e32 v47, v32
	s_branch .LBB0_170
